# combo3 + software-pipelined P0 modulation GEMV (double-buffered global loads, vmcnt(8))
# baseline (speedup 1.0000x reference)
; __global__ void __launch_bounds__(NTHREADS, 2) mega_fwd(Params P) {
;     ...
;             if (qi < DEPTH * 24) {
;                 const int l2 = qi / 24, cg4 = qi % 24, n4 = 256 * cg4 + 4 * lane;
;                 const float* W = P.w_mod + (size_t)l2 * DM * NMOD + n4;
;                 f32x4 a0 = {0.f, 0.f, 0.f, 0.f}, a1 = a0, a2 = a0;
; #pragma unroll 8
;                 for (int kk = 0; kk < 128; ++kk) { const int k = wid * 128 + kk; const f32x4 wv = __builtin_nontemporal_load((const f32x4*)(W + (size_t)k * NMOD)); a0 += wv * scv[k]; a1 += wv * scv[DM + k]; a2 += wv * scv[2 * DM + k]; }
.LBB0_89:
	s_andn2_b64 vcc, exec, s[0:1]
	s_cbranch_vccnz .LBB0_42
	s_mul_hi_i32 s0, s14, 0x2aaaaaab
	s_lshr_b32 s1, s0, 31
	s_ashr_i32 s0, s0, 2
	s_add_i32 s10, s0, s1
	s_mul_i32 s0, s10, 24
	s_sub_i32 s0, s14, s0
	s_lshl_b32 s8, s0, 8
	s_mul_i32 s0, s10, 0x1800000
	v_or_b32_e32 v2, s8, v38
	s_mul_hi_i32 s1, s10, 0x1800000
	s_add_u32 s0, s20, s0
	v_ashrrev_i32_e32 v3, 31, v2
	s_addc_u32 s1, s21, s1
	v_lshl_add_u64 v[14:15], v[2:3], 2, s[0:1]
	v_mov_b32_e32 v2, 0
	s_movk_i32 s9, 0xfe00
	v_mov_b32_e32 v3, v2
	v_mov_b32_e32 v4, v2
	v_mov_b32_e32 v5, v2
	v_mov_b32_e32 v6, v2
	v_mov_b32_e32 v7, v2
	v_mov_b32_e32 v8, v2
	v_mov_b32_e32 v9, v2
	v_mov_b32_e32 v10, v2
	v_mov_b32_e32 v11, v2
	v_mov_b32_e32 v12, v2
	v_mov_b32_e32 v13, v2
	v_add_co_u32_e64 v16, s[0:1], s35, v14
	v_add_co_u32_e32 v36, vcc, 0xfffd6000, v14
	s_nop 0
	v_addc_co_u32_e64 v17, s[0:1], -1, v15, s[0:1]
	v_add_co_u32_e64 v20, s[0:1], s37, v14
	v_addc_co_u32_e32 v37, vcc, -1, v15, vcc
	s_nop 0
	v_addc_co_u32_e64 v21, s[0:1], -1, v15, s[0:1]
	v_add_co_u32_e64 v24, s[0:1], s38, v14
	s_nop 1
	v_addc_co_u32_e64 v25, s[0:1], -1, v15, s[0:1]
	v_add_co_u32_e64 v28, s[0:1], s39, v14
	s_nop 1
	v_addc_co_u32_e64 v29, s[0:1], -1, v15, s[0:1]
	v_add_co_u32_e64 v32, s[0:1], s40, v14
	s_nop 1
	v_addc_co_u32_e64 v33, s[0:1], -1, v15, s[0:1]
	v_add_co_u32_e64 v64, s[0:1], s41, v14
	s_nop 1
	v_addc_co_u32_e64 v65, s[0:1], -1, v15, s[0:1]
	global_load_dwordx4 v[16:19], v[16:17], off nt
	s_nop 0
	global_load_dwordx4 v[20:23], v[20:21], off nt
	s_nop 0
	global_load_dwordx4 v[24:27], v[24:25], off nt
	s_nop 0
	global_load_dwordx4 v[28:31], v[28:29], off nt
	s_nop 0
	global_load_dwordx4 v[32:35], v[32:33], off nt
	s_nop 0
	global_load_dwordx4 v[60:63], v[36:37], off nt
	global_load_dwordx4 v[90:93], v[64:65], off nt
	global_load_dwordx4 v[94:97], v[14:15], off nt
	v_lshl_add_u64 v[14:15], v[14:15], 0, s[12:13]
.Lgemv_loop:
	v_add_co_u32_e64 v128, s[0:1], s35, v14
	v_add_co_u32_e32 v160, vcc, 0xfffd6000, v14
	s_nop 0
	v_addc_co_u32_e64 v129, s[0:1], -1, v15, s[0:1]
	v_add_co_u32_e64 v132, s[0:1], s37, v14
	v_addc_co_u32_e32 v161, vcc, -1, v15, vcc
	s_nop 0
	v_addc_co_u32_e64 v133, s[0:1], -1, v15, s[0:1]
	v_add_co_u32_e64 v136, s[0:1], s38, v14
	s_nop 1
	v_addc_co_u32_e64 v137, s[0:1], -1, v15, s[0:1]
	v_add_co_u32_e64 v140, s[0:1], s39, v14
	s_nop 1
	v_addc_co_u32_e64 v141, s[0:1], -1, v15, s[0:1]
	v_add_co_u32_e64 v144, s[0:1], s40, v14
	s_nop 1
	v_addc_co_u32_e64 v145, s[0:1], -1, v15, s[0:1]
	v_add_co_u32_e64 v164, s[0:1], s41, v14
	s_nop 1
	v_addc_co_u32_e64 v165, s[0:1], -1, v15, s[0:1]
	global_load_dwordx4 v[128:131], v[128:129], off nt
	s_nop 0
	global_load_dwordx4 v[132:135], v[132:133], off nt
	s_nop 0
	global_load_dwordx4 v[136:139], v[136:137], off nt
	s_nop 0
	global_load_dwordx4 v[140:143], v[140:141], off nt
	s_nop 0
	global_load_dwordx4 v[144:147], v[144:145], off nt
	s_nop 0
	global_load_dwordx4 v[160:163], v[160:161], off nt
	global_load_dwordx4 v[164:167], v[164:165], off nt
	global_load_dwordx4 v[168:171], v[14:15], off nt
	v_lshl_add_u64 v[14:15], v[14:15], 0, s[12:13]
	s_add_i32 s0, s18, s9
	s_add_i32 s1, s0, 0x11200
	s_add_i32 s14, s0, 0x12200
	s_add_i32 s15, s0, 0x13200
	s_add_i32 s42, s0, 0x11210
	s_add_i32 s43, s0, 0x12210
	s_add_i32 s0, s0, 0x13210
	v_mov_b32_e32 v36, s1
	v_mov_b32_e32 v118, s0
	v_mov_b32_e32 v37, s14
	v_mov_b32_e32 v40, s15
	v_mov_b32_e32 v64, s42
	v_mov_b32_e32 v65, s43
	ds_read_b128 v[98:101], v36
	ds_read_b128 v[102:105], v37
	ds_read_b128 v[106:109], v40
	ds_read_b128 v[110:113], v64
	ds_read_b128 v[114:117], v65
	ds_read_b128 v[118:121], v118
	s_waitcnt lgkmcnt(0)
	v_mov_b32_e32 v36, v101
	v_mov_b32_e32 v40, v105
	v_mov_b32_e32 v64, v109
	s_add_i32 s9, s9, 32
	v_mov_b32_e32 v122, v113
	v_mov_b32_e32 v124, v117
	v_mov_b32_e32 v126, v121
	s_waitcnt vmcnt(8)
	v_pk_fma_f32 v[4:5], v[62:63], v[98:99], v[4:5] op_sel_hi:[1,0,1]
	v_pk_fma_f32 v[2:3], v[60:61], v[98:99], v[2:3] op_sel_hi:[1,0,1]
	v_pk_fma_f32 v[8:9], v[62:63], v[102:103], v[8:9] op_sel_hi:[1,0,1]
	v_pk_fma_f32 v[6:7], v[60:61], v[102:103], v[6:7] op_sel_hi:[1,0,1]
	v_pk_fma_f32 v[12:13], v[62:63], v[106:107], v[12:13] op_sel_hi:[1,0,1]
	v_pk_fma_f32 v[10:11], v[60:61], v[106:107], v[10:11] op_sel_hi:[1,0,1]
	v_pk_fma_f32 v[4:5], v[18:19], v[98:99], v[4:5] op_sel:[0,1,0]
	v_pk_fma_f32 v[2:3], v[16:17], v[98:99], v[2:3] op_sel:[0,1,0]
	v_pk_fma_f32 v[8:9], v[18:19], v[102:103], v[8:9] op_sel:[0,1,0]
	v_pk_fma_f32 v[6:7], v[16:17], v[102:103], v[6:7] op_sel:[0,1,0]
	v_pk_fma_f32 v[12:13], v[18:19], v[106:107], v[12:13] op_sel:[0,1,0]
	v_pk_fma_f32 v[10:11], v[16:17], v[106:107], v[10:11] op_sel:[0,1,0]
	v_pk_fma_f32 v[4:5], v[22:23], v[100:101], v[4:5] op_sel_hi:[1,0,1]
	v_pk_fma_f32 v[2:3], v[20:21], v[100:101], v[2:3] op_sel_hi:[1,0,1]
	v_pk_fma_f32 v[8:9], v[22:23], v[104:105], v[8:9] op_sel_hi:[1,0,1]
	v_pk_fma_f32 v[6:7], v[20:21], v[104:105], v[6:7] op_sel_hi:[1,0,1]
	v_pk_fma_f32 v[12:13], v[22:23], v[108:109], v[12:13] op_sel_hi:[1,0,1]
	v_pk_fma_f32 v[10:11], v[20:21], v[108:109], v[10:11] op_sel_hi:[1,0,1]
	v_pk_fma_f32 v[4:5], v[26:27], v[36:37], v[4:5] op_sel_hi:[1,0,1]
	v_pk_fma_f32 v[2:3], v[24:25], v[36:37], v[2:3] op_sel_hi:[1,0,1]
	v_pk_fma_f32 v[8:9], v[26:27], v[40:41], v[8:9] op_sel_hi:[1,0,1]
	v_pk_fma_f32 v[6:7], v[24:25], v[40:41], v[6:7] op_sel_hi:[1,0,1]
	v_pk_fma_f32 v[12:13], v[26:27], v[64:65], v[12:13] op_sel_hi:[1,0,1]
	v_pk_fma_f32 v[10:11], v[24:25], v[64:65], v[10:11] op_sel_hi:[1,0,1]
	v_pk_fma_f32 v[4:5], v[30:31], v[110:111], v[4:5] op_sel_hi:[1,0,1]
	v_pk_fma_f32 v[2:3], v[28:29], v[110:111], v[2:3] op_sel_hi:[1,0,1]
	v_pk_fma_f32 v[8:9], v[30:31], v[114:115], v[8:9] op_sel_hi:[1,0,1]
; __global__ void __launch_bounds__(NTHREADS, 2) mega_fwd(Params P) {
;     ...
;                 f32x4 a0 = {0.f, 0.f, 0.f, 0.f}, a1 = a0, a2 = a0;
; #pragma unroll 8
;                 for (int kk = 0; kk < 128; ++kk) { const int k = wid * 128 + kk; const f32x4 wv = __builtin_nontemporal_load((const f32x4*)(W + (size_t)k * NMOD)); a0 += wv * scv[k]; a1 += wv * scv[DM + k]; a2 += wv * scv[2 * DM + k]; }
	v_pk_fma_f32 v[6:7], v[28:29], v[114:115], v[6:7] op_sel_hi:[1,0,1]
	v_pk_fma_f32 v[12:13], v[30:31], v[118:119], v[12:13] op_sel_hi:[1,0,1]
	v_pk_fma_f32 v[10:11], v[28:29], v[118:119], v[10:11] op_sel_hi:[1,0,1]
	v_pk_fma_f32 v[4:5], v[34:35], v[110:111], v[4:5] op_sel:[0,1,0]
	v_pk_fma_f32 v[2:3], v[32:33], v[110:111], v[2:3] op_sel:[0,1,0]
	v_pk_fma_f32 v[8:9], v[34:35], v[114:115], v[8:9] op_sel:[0,1,0]
	v_pk_fma_f32 v[6:7], v[32:33], v[114:115], v[6:7] op_sel:[0,1,0]
	v_pk_fma_f32 v[12:13], v[34:35], v[118:119], v[12:13] op_sel:[0,1,0]
	v_pk_fma_f32 v[10:11], v[32:33], v[118:119], v[10:11] op_sel:[0,1,0]
	v_pk_fma_f32 v[4:5], v[92:93], v[112:113], v[4:5] op_sel_hi:[1,0,1]
	v_pk_fma_f32 v[2:3], v[90:91], v[112:113], v[2:3] op_sel_hi:[1,0,1]
	v_pk_fma_f32 v[8:9], v[92:93], v[116:117], v[8:9] op_sel_hi:[1,0,1]
	v_pk_fma_f32 v[6:7], v[90:91], v[116:117], v[6:7] op_sel_hi:[1,0,1]
	v_pk_fma_f32 v[12:13], v[92:93], v[120:121], v[12:13] op_sel_hi:[1,0,1]
	v_pk_fma_f32 v[10:11], v[90:91], v[120:121], v[10:11] op_sel_hi:[1,0,1]
	v_pk_fma_f32 v[4:5], v[96:97], v[122:123], v[4:5] op_sel_hi:[1,0,1]
	v_pk_fma_f32 v[2:3], v[94:95], v[122:123], v[2:3] op_sel_hi:[1,0,1]
	v_pk_fma_f32 v[8:9], v[96:97], v[124:125], v[8:9] op_sel_hi:[1,0,1]
	v_pk_fma_f32 v[6:7], v[94:95], v[124:125], v[6:7] op_sel_hi:[1,0,1]
	v_pk_fma_f32 v[12:13], v[96:97], v[126:127], v[12:13] op_sel_hi:[1,0,1]
	v_pk_fma_f32 v[10:11], v[94:95], v[126:127], v[10:11] op_sel_hi:[1,0,1]
	s_cmp_lg_u32 s9, 0xffffffe0
	s_cbranch_scc0 .Lgemv_nopf
	v_add_co_u32_e64 v16, s[0:1], s35, v14
	v_add_co_u32_e32 v36, vcc, 0xfffd6000, v14
	s_nop 0
	v_addc_co_u32_e64 v17, s[0:1], -1, v15, s[0:1]
	v_add_co_u32_e64 v20, s[0:1], s37, v14
	v_addc_co_u32_e32 v37, vcc, -1, v15, vcc
	s_nop 0
	v_addc_co_u32_e64 v21, s[0:1], -1, v15, s[0:1]
	v_add_co_u32_e64 v24, s[0:1], s38, v14
	s_nop 1
	v_addc_co_u32_e64 v25, s[0:1], -1, v15, s[0:1]
	v_add_co_u32_e64 v28, s[0:1], s39, v14
	s_nop 1
	v_addc_co_u32_e64 v29, s[0:1], -1, v15, s[0:1]
	v_add_co_u32_e64 v32, s[0:1], s40, v14
	s_nop 1
	v_addc_co_u32_e64 v33, s[0:1], -1, v15, s[0:1]
	v_add_co_u32_e64 v64, s[0:1], s41, v14
	s_nop 1
	v_addc_co_u32_e64 v65, s[0:1], -1, v15, s[0:1]
	global_load_dwordx4 v[16:19], v[16:17], off nt
	s_nop 0
	global_load_dwordx4 v[20:23], v[20:21], off nt
	s_nop 0
	global_load_dwordx4 v[24:27], v[24:25], off nt
	s_nop 0
	global_load_dwordx4 v[28:31], v[28:29], off nt
	s_nop 0
	global_load_dwordx4 v[32:35], v[32:33], off nt
	s_nop 0
	global_load_dwordx4 v[60:63], v[36:37], off nt
	global_load_dwordx4 v[90:93], v[64:65], off nt
	global_load_dwordx4 v[94:97], v[14:15], off nt
	v_lshl_add_u64 v[14:15], v[14:15], 0, s[12:13]
	s_add_i32 s0, s18, s9
	s_add_i32 s1, s0, 0x11200
	s_add_i32 s14, s0, 0x12200
	s_add_i32 s15, s0, 0x13200
	s_add_i32 s42, s0, 0x11210
	s_add_i32 s43, s0, 0x12210
	s_add_i32 s0, s0, 0x13210
	v_mov_b32_e32 v36, s1
	v_mov_b32_e32 v118, s0
	v_mov_b32_e32 v37, s14
	v_mov_b32_e32 v40, s15
	v_mov_b32_e32 v64, s42
	v_mov_b32_e32 v65, s43
	ds_read_b128 v[98:101], v36
	ds_read_b128 v[102:105], v37
	ds_read_b128 v[106:109], v40
	ds_read_b128 v[110:113], v64
	ds_read_b128 v[114:117], v65
	ds_read_b128 v[118:121], v118
	s_waitcnt lgkmcnt(0)
	v_mov_b32_e32 v36, v101
	v_mov_b32_e32 v40, v105
	v_mov_b32_e32 v64, v109
	s_add_i32 s9, s9, 32
	v_mov_b32_e32 v122, v113
	v_mov_b32_e32 v124, v117
	v_mov_b32_e32 v126, v121
	s_waitcnt vmcnt(8)
	s_branch .Lgemv_fmaB
.Lgemv_nopf:
	s_add_i32 s0, s18, s9
	s_add_i32 s1, s0, 0x11200
	s_add_i32 s14, s0, 0x12200
	s_add_i32 s15, s0, 0x13200
	s_add_i32 s42, s0, 0x11210
	s_add_i32 s43, s0, 0x12210
	s_add_i32 s0, s0, 0x13210
	v_mov_b32_e32 v36, s1
	v_mov_b32_e32 v118, s0
	v_mov_b32_e32 v37, s14
	v_mov_b32_e32 v40, s15
	v_mov_b32_e32 v64, s42
	v_mov_b32_e32 v65, s43
	ds_read_b128 v[98:101], v36
	ds_read_b128 v[102:105], v37
	ds_read_b128 v[106:109], v40
	ds_read_b128 v[110:113], v64
	ds_read_b128 v[114:117], v65
	ds_read_b128 v[118:121], v118
	s_waitcnt lgkmcnt(0)
	v_mov_b32_e32 v36, v101
	v_mov_b32_e32 v40, v105
	v_mov_b32_e32 v64, v109
	s_add_i32 s9, s9, 32
	v_mov_b32_e32 v122, v113
	v_mov_b32_e32 v124, v117
	v_mov_b32_e32 v126, v121
	s_waitcnt vmcnt(0)
; #define LAS __attribute__((address_space(3)))
; __global__ void __launch_bounds__(NTHREADS, 2) mega_fwd(Params P) {
;     ...
;                 for (int kk = 0; kk < 128; ++kk) { const int k = wid * 128 + kk; const f32x4 wv = __builtin_nontemporal_load((const f32x4*)(W + (size_t)k * NMOD)); a0 += wv * scv[k]; a1 += wv * scv[DM + k]; a2 += wv * scv[2 * DM + k]; }
;                 LAS f32x4* red4 = (LAS f32x4*)red;
;                 red4[(wid * 3 + 0) * 64 + lane] = a0; red4[(wid * 3 + 1) * 64 + lane] = a1; red4[(wid * 3 + 2) * 64 + lane] = a2;
;                 __syncthreads();
;                 for (int o = tid; o < 768; o += NTHREADS) { const int v = o >> 8, col = o & 255; float sacc = P.b_mod[(size_t)l2 * NMOD + 256 * cg4 + col];
; #pragma unroll
;                     for (int w2 = 0; w2 < 8; ++w2) sacc += red[(w2 * 3 + v) * 256 + col];
;                     mod[(size_t)(l2 * 3 + v) * NMOD + 256 * cg4 + col] = sacc; }
.Lgemv_fmaB:
	v_pk_fma_f32 v[4:5], v[162:163], v[98:99], v[4:5] op_sel_hi:[1,0,1]
	v_pk_fma_f32 v[2:3], v[160:161], v[98:99], v[2:3] op_sel_hi:[1,0,1]
	v_pk_fma_f32 v[8:9], v[162:163], v[102:103], v[8:9] op_sel_hi:[1,0,1]
	v_pk_fma_f32 v[6:7], v[160:161], v[102:103], v[6:7] op_sel_hi:[1,0,1]
	v_pk_fma_f32 v[12:13], v[162:163], v[106:107], v[12:13] op_sel_hi:[1,0,1]
	v_pk_fma_f32 v[10:11], v[160:161], v[106:107], v[10:11] op_sel_hi:[1,0,1]
	v_pk_fma_f32 v[4:5], v[130:131], v[98:99], v[4:5] op_sel:[0,1,0]
	v_pk_fma_f32 v[2:3], v[128:129], v[98:99], v[2:3] op_sel:[0,1,0]
	v_pk_fma_f32 v[8:9], v[130:131], v[102:103], v[8:9] op_sel:[0,1,0]
	v_pk_fma_f32 v[6:7], v[128:129], v[102:103], v[6:7] op_sel:[0,1,0]
	v_pk_fma_f32 v[12:13], v[130:131], v[106:107], v[12:13] op_sel:[0,1,0]
	v_pk_fma_f32 v[10:11], v[128:129], v[106:107], v[10:11] op_sel:[0,1,0]
	v_pk_fma_f32 v[4:5], v[134:135], v[100:101], v[4:5] op_sel_hi:[1,0,1]
	v_pk_fma_f32 v[2:3], v[132:133], v[100:101], v[2:3] op_sel_hi:[1,0,1]
	v_pk_fma_f32 v[8:9], v[134:135], v[104:105], v[8:9] op_sel_hi:[1,0,1]
	v_pk_fma_f32 v[6:7], v[132:133], v[104:105], v[6:7] op_sel_hi:[1,0,1]
	v_pk_fma_f32 v[12:13], v[134:135], v[108:109], v[12:13] op_sel_hi:[1,0,1]
	v_pk_fma_f32 v[10:11], v[132:133], v[108:109], v[10:11] op_sel_hi:[1,0,1]
	v_pk_fma_f32 v[4:5], v[138:139], v[36:37], v[4:5] op_sel_hi:[1,0,1]
	v_pk_fma_f32 v[2:3], v[136:137], v[36:37], v[2:3] op_sel_hi:[1,0,1]
	v_pk_fma_f32 v[8:9], v[138:139], v[40:41], v[8:9] op_sel_hi:[1,0,1]
	v_pk_fma_f32 v[6:7], v[136:137], v[40:41], v[6:7] op_sel_hi:[1,0,1]
	v_pk_fma_f32 v[12:13], v[138:139], v[64:65], v[12:13] op_sel_hi:[1,0,1]
	v_pk_fma_f32 v[10:11], v[136:137], v[64:65], v[10:11] op_sel_hi:[1,0,1]
	v_pk_fma_f32 v[4:5], v[142:143], v[110:111], v[4:5] op_sel_hi:[1,0,1]
	v_pk_fma_f32 v[2:3], v[140:141], v[110:111], v[2:3] op_sel_hi:[1,0,1]
	v_pk_fma_f32 v[8:9], v[142:143], v[114:115], v[8:9] op_sel_hi:[1,0,1]
	v_pk_fma_f32 v[6:7], v[140:141], v[114:115], v[6:7] op_sel_hi:[1,0,1]
	v_pk_fma_f32 v[12:13], v[142:143], v[118:119], v[12:13] op_sel_hi:[1,0,1]
	v_pk_fma_f32 v[10:11], v[140:141], v[118:119], v[10:11] op_sel_hi:[1,0,1]
	v_pk_fma_f32 v[4:5], v[146:147], v[110:111], v[4:5] op_sel:[0,1,0]
	v_pk_fma_f32 v[2:3], v[144:145], v[110:111], v[2:3] op_sel:[0,1,0]
	v_pk_fma_f32 v[8:9], v[146:147], v[114:115], v[8:9] op_sel:[0,1,0]
	v_pk_fma_f32 v[6:7], v[144:145], v[114:115], v[6:7] op_sel:[0,1,0]
	v_pk_fma_f32 v[12:13], v[146:147], v[118:119], v[12:13] op_sel:[0,1,0]
	v_pk_fma_f32 v[10:11], v[144:145], v[118:119], v[10:11] op_sel:[0,1,0]
	v_pk_fma_f32 v[4:5], v[166:167], v[112:113], v[4:5] op_sel_hi:[1,0,1]
	v_pk_fma_f32 v[2:3], v[164:165], v[112:113], v[2:3] op_sel_hi:[1,0,1]
	v_pk_fma_f32 v[8:9], v[166:167], v[116:117], v[8:9] op_sel_hi:[1,0,1]
	v_pk_fma_f32 v[6:7], v[164:165], v[116:117], v[6:7] op_sel_hi:[1,0,1]
	v_pk_fma_f32 v[12:13], v[166:167], v[120:121], v[12:13] op_sel_hi:[1,0,1]
	v_pk_fma_f32 v[10:11], v[164:165], v[120:121], v[10:11] op_sel_hi:[1,0,1]
	v_pk_fma_f32 v[4:5], v[170:171], v[122:123], v[4:5] op_sel_hi:[1,0,1]
	v_pk_fma_f32 v[2:3], v[168:169], v[122:123], v[2:3] op_sel_hi:[1,0,1]
	v_pk_fma_f32 v[8:9], v[170:171], v[124:125], v[8:9] op_sel_hi:[1,0,1]
	v_pk_fma_f32 v[6:7], v[168:169], v[124:125], v[6:7] op_sel_hi:[1,0,1]
	v_pk_fma_f32 v[12:13], v[170:171], v[126:127], v[12:13] op_sel_hi:[1,0,1]
	v_pk_fma_f32 v[10:11], v[168:169], v[126:127], v[10:11] op_sel_hi:[1,0,1]
	s_cmp_eq_u32 s9, 0
	s_cbranch_scc0 .Lgemv_loop
	ds_write_b128 v69, v[2:5]
	ds_write_b128 v69, v[6:9] offset:1024
	ds_write_b128 v69, v[10:13] offset:2048
	s_waitcnt lgkmcnt(0)
	s_barrier
	s_and_saveexec_b64 s[0:1], s[4:5]
	s_cbranch_execz .LBB0_41
	v_readlane_b32 s44, v253, 9
	s_ashr_i32 s9, s8, 31
	s_mul_i32 s15, s10, 0x6000
	v_readlane_b32 s54, v253, 19
	s_mul_hi_i32 s14, s10, 0x6000
	v_readlane_b32 s55, v253, 20
	s_add_u32 s42, s54, s15
	s_addc_u32 s43, s55, s14
	s_lshl_b64 s[14:15], s[8:9], 2
	s_add_u32 s14, s42, s14
	s_addc_u32 s15, s43, s15
	v_lshlrev_b32_e32 v40, 2, v58
	s_mul_i32 s10, s10, 3
	v_lshl_add_u64 v[2:3], s[14:15], 0, v[40:41]
	s_mov_b64 s[14:15], 0
	v_mov_b32_e32 v4, v1
	v_readlane_b32 s45, v253, 10
	v_readlane_b32 s46, v253, 11
	v_readlane_b32 s47, v253, 12
	v_readlane_b32 s48, v253, 13
	v_readlane_b32 s49, v253, 14
	v_readlane_b32 s50, v253, 15
	v_readlane_b32 s51, v253, 16
	v_readlane_b32 s52, v253, 17
	v_readlane_b32 s53, v253, 18
	v_readlane_b32 s56, v253, 21
	v_readlane_b32 s57, v253, 22
	v_readlane_b32 s58, v253, 23
	v_readlane_b32 s59, v253, 24
